# up GEMM epilogue: the eight per-row scale loads issued up front with one wait, instead of a load + full drain before every row
# speedup vs baseline: 1.0096x; 1.0069x over previous
; #define PG8_STAGE(bufoff, gbase, voff) do { _Pragma("unroll") for (int _i = 0; _i < 2; ++_i) \
;         __builtin_amdgcn_global_load_lds((const unsigned*)((const char*)(gbase) + (voff)[_i]), (LAS unsigned*)(lds + (bufoff) + ldsw + _i * 8192), 16, 0, 0); } while (0)
; #define PG8_LDA(dst, b, h) do { _Pragma("unroll") for (int m = 0; m < 4; ++m) _Pragma("unroll") for (int k = 0; k < 2; ++k) dst[m][k] = *(const LAS bf16x8*)(lds + PG8_SA(b, h) + aoff + m * 2048 + k * 1024); } while (0)
; #define PG8_WAIT_V(n) asm volatile("s_waitcnt vmcnt(" #n ")" ::: "memory")
; #define PG8_WAIT_L(n) asm volatile("s_waitcnt lgkmcnt(" #n ")" ::: "memory")
; template <class Epi>
; __device__ __forceinline__ void gemm_phase(LAS unsigned char* lds, const Gemm g, const StaticOrder& S, const Epi& E) {
;     ...
;         for (int t = 0; t < nt; t += 2) {
;             const bool last = (t == nt - 2);
;             const char* a1 = cA + (size_t)(t + 1) * kstep;
;             const char* a2 = last ? nA : cA + (size_t)(t + 2) * kstep; const char* b2 = last ? nB : cB + (size_t)(t + 2) * kstep;
;             const char* a3 = a2 + kstep; const char* b3 = b2 + kstep;
;             PG8_LDB(B0, 0, 0); PG8_SCHED; PG8_LDA(At, 0, 0); PG8_STAGE(PG8_SA(1, 1), a1 + hstep, voffA);
;             PG8_WAIT_L(8); PG8_BAR; PG8_WAIT_L(0); PG8_MMA(0, 0, At, B0); PG8_BAR; PG8_SCHED;
;             PG8_LDB(B1, 0, 1); PG8_STAGE(PG8_SB(0, 0), b2, voffB);
;             PG8_BAR; PG8_WAIT_L(0); PG8_MMA(0, 1, At, B1); PG8_BAR;
;             PG8_LDA(At, 0, 1); PG8_STAGE(PG8_SA(0, 0), a2, voffA);
;             PG8_BAR; PG8_WAIT_L(0); PG8_MMA(1, 0, At, B0); PG8_BAR; PG8_SCHED;
;             PG8_STAGE(PG8_SB(0, 1), b2 + hstep, voffB);
;             PG8_WAIT_V(6); PG8_BAR; PG8_MMA(1, 1, At, B1); PG8_BAR;
;             PG8_LDB(B0, 1, 0); PG8_SCHED; PG8_LDA(At, 1, 0); PG8_STAGE(PG8_SA(0, 1), a2 + hstep, voffA);
;             PG8_WAIT_L(8); PG8_BAR; PG8_WAIT_L(0); PG8_MMA(0, 0, At, B0); PG8_BAR; PG8_SCHED;
;             PG8_LDB(B1, 1, 1); PG8_STAGE(PG8_SB(1, 0), b3, voffB);
;             PG8_BAR; PG8_WAIT_L(0); PG8_MMA(0, 1, At, B1); PG8_BAR;
;             PG8_LDA(At, 1, 1); PG8_STAGE(PG8_SA(1, 0), a3, voffA);
;             PG8_BAR; PG8_WAIT_L(0); PG8_MMA(1, 0, At, B0); PG8_BAR; PG8_SCHED;
;             PG8_STAGE(PG8_SB(1, 1), b3 + hstep, voffB);
;             PG8_WAIT_V(6); PG8_BAR; PG8_MMA(1, 1, At, B1); PG8_BAR;
.LBB0_98:
	s_add_u32 s22, s20, 0xfff80080
	s_addc_u32 s23, s21, -1
	s_add_i32 s48, 0, 0x10000
	v_add_u32_e32 v146, s48, v163
	ds_read_b128 v[142:145], v146
	ds_read_b128 v[174:177], v146 offset:1024
	ds_read_b128 v[178:181], v146 offset:2048
	ds_read_b128 v[182:185], v146 offset:3072
	s_cmp_eq_u32 s47, 28
	s_cselect_b32 s25, s13, s23
	s_cselect_b32 s24, s42, s22
	s_cselect_b32 s23, s9, s46
	s_cselect_b32 s22, s43, s44
	v_lshl_add_u64 v[146:147], s[20:21], 0, v[138:139]
	s_add_i32 m0, s19, 0xc000
	ds_read_b128 v[186:189], v173
	ds_read_b128 v[190:193], v173 offset:1024
	ds_read_b128 v[194:197], v173 offset:2048
	ds_read_b128 v[198:201], v173 offset:3072
	ds_read_b128 v[214:217], v173 offset:4096
	ds_read_b128 v[218:221], v173 offset:5120
	ds_read_b128 v[222:225], v173 offset:6144
	ds_read_b128 v[226:229], v173 offset:7168
	global_load_lds_dwordx4 v[146:147], off
	v_lshl_add_u64 v[146:147], s[20:21], 0, v[140:141]
	s_add_i32 m0, s19, 0xe000
	s_nop 0
	global_load_lds_dwordx4 v[146:147], off
	s_waitcnt lgkmcnt(8)
	s_barrier
	s_waitcnt lgkmcnt(0)
	s_setprio 1
	s_waitcnt lgkmcnt(0)
	v_mfma_f32_16x16x32_bf16 v[128:131], v[142:145], v[186:189], v[128:131]
	v_mfma_f32_16x16x32_bf16 v[124:127], v[178:181], v[186:189], v[124:127]
	v_mfma_f32_16x16x32_bf16 v[112:115], v[142:145], v[194:197], v[112:115]
	v_mfma_f32_16x16x32_bf16 v[108:111], v[178:181], v[194:197], v[108:111]
	v_mfma_f32_16x16x32_bf16 v[96:99], v[142:145], v[214:217], v[96:99]
	v_mfma_f32_16x16x32_bf16 v[92:95], v[178:181], v[214:217], v[92:95]
	v_mfma_f32_16x16x32_bf16 v[80:83], v[142:145], v[222:225], v[80:83]
	v_mfma_f32_16x16x32_bf16 v[76:79], v[178:181], v[222:225], v[76:79]
	v_mfma_f32_16x16x32_bf16 v[128:131], v[174:177], v[190:193], v[128:131]
	v_mfma_f32_16x16x32_bf16 v[124:127], v[182:185], v[190:193], v[124:127]
	v_mfma_f32_16x16x32_bf16 v[112:115], v[174:177], v[198:201], v[112:115]
	v_mfma_f32_16x16x32_bf16 v[108:111], v[182:185], v[198:201], v[108:111]
	v_mfma_f32_16x16x32_bf16 v[96:99], v[174:177], v[218:221], v[96:99]
	v_mfma_f32_16x16x32_bf16 v[92:95], v[182:185], v[218:221], v[92:95]
	v_mfma_f32_16x16x32_bf16 v[80:83], v[174:177], v[226:229], v[80:83]
	v_mfma_f32_16x16x32_bf16 v[76:79], v[182:185], v[226:229], v[76:79]
	s_setprio 0
	s_barrier
	s_add_i32 s52, 0, 0x14000
	v_add_u32_e32 v146, s52, v163
	s_add_i32 s48, s48, s31
	ds_read_b128 v[230:233], v146
	ds_read_b128 v[234:237], v146 offset:1024
	ds_read_b128 v[238:241], v146 offset:2048
	ds_read_b128 v[242:245], v146 offset:3072
	v_lshl_add_u64 v[146:147], s[22:23], 0, v[148:149]
	s_mov_b32 m0, s48
	v_lshl_add_u64 v[170:171], s[22:23], 0, v[136:137]
	global_load_lds_dwordx4 v[146:147], off
	s_add_i32 m0, s48, 0x2000
	s_nop 0
	global_load_lds_dwordx4 v[170:171], off
	s_barrier
	s_waitcnt lgkmcnt(0)
	s_setprio 1
	s_waitcnt lgkmcnt(0)
	v_mfma_f32_16x16x32_bf16 v[120:123], v[230:233], v[186:189], v[120:123]
	v_mfma_f32_16x16x32_bf16 v[116:119], v[238:241], v[186:189], v[116:119]
	v_mfma_f32_16x16x32_bf16 v[104:107], v[230:233], v[194:197], v[104:107]
	v_mfma_f32_16x16x32_bf16 v[100:103], v[238:241], v[194:197], v[100:103]
	v_mfma_f32_16x16x32_bf16 v[88:91], v[230:233], v[214:217], v[88:91]
	v_mfma_f32_16x16x32_bf16 v[84:87], v[238:241], v[214:217], v[84:87]
	v_mfma_f32_16x16x32_bf16 v[72:75], v[230:233], v[222:225], v[72:75]
	v_mfma_f32_16x16x32_bf16 v[68:71], v[238:241], v[222:225], v[68:71]
	v_mfma_f32_16x16x32_bf16 v[120:123], v[234:237], v[190:193], v[120:123]
	v_mfma_f32_16x16x32_bf16 v[116:119], v[242:245], v[190:193], v[116:119]
	v_mfma_f32_16x16x32_bf16 v[104:107], v[234:237], v[198:201], v[104:107]
	v_mfma_f32_16x16x32_bf16 v[100:103], v[242:245], v[198:201], v[100:103]
	v_mfma_f32_16x16x32_bf16 v[88:91], v[234:237], v[218:221], v[88:91]
	v_mfma_f32_16x16x32_bf16 v[84:87], v[242:245], v[218:221], v[84:87]
	v_mfma_f32_16x16x32_bf16 v[72:75], v[234:237], v[226:229], v[72:75]
	v_mfma_f32_16x16x32_bf16 v[68:71], v[242:245], v[226:229], v[68:71]
	s_setprio 0
	s_mov_b32 m0, s19
	v_lshl_add_u64 v[246:247], s[24:25], 0, v[132:133]
	s_barrier
	ds_read_b128 v[186:189], v173 offset:16384
	ds_read_b128 v[190:193], v173 offset:17408
	ds_read_b128 v[194:197], v173 offset:18432
	ds_read_b128 v[198:201], v173 offset:19456
	ds_read_b128 v[214:217], v173 offset:20480
	ds_read_b128 v[218:221], v173 offset:21504
	ds_read_b128 v[222:225], v173 offset:22528
	ds_read_b128 v[226:229], v173 offset:23552
	global_load_lds_dwordx4 v[246:247], off
	v_lshl_add_u64 v[248:249], s[24:25], 0, v[134:135]
	s_mov_b32 m0, s33
	s_nop 0
	global_load_lds_dwordx4 v[248:249], off
	s_barrier
	s_waitcnt lgkmcnt(0)
	s_setprio 1
	s_waitcnt lgkmcnt(0)
	v_mfma_f32_16x16x32_bf16 v[64:67], v[142:145], v[186:189], v[64:67]
	v_mfma_f32_16x16x32_bf16 v[60:63], v[178:181], v[186:189], v[60:63]
	v_mfma_f32_16x16x32_bf16 v[48:51], v[142:145], v[194:197], v[48:51]
	v_mfma_f32_16x16x32_bf16 v[44:47], v[178:181], v[194:197], v[44:47]
	v_mfma_f32_16x16x32_bf16 v[32:35], v[142:145], v[214:217], v[32:35]
	v_mfma_f32_16x16x32_bf16 v[28:31], v[178:181], v[214:217], v[28:31]
	v_mfma_f32_16x16x32_bf16 v[16:19], v[142:145], v[222:225], v[16:19]
	v_mfma_f32_16x16x32_bf16 v[12:15], v[178:181], v[222:225], v[12:15]
	v_mfma_f32_16x16x32_bf16 v[64:67], v[174:177], v[190:193], v[64:67]
	v_mfma_f32_16x16x32_bf16 v[60:63], v[182:185], v[190:193], v[60:63]
	v_mfma_f32_16x16x32_bf16 v[48:51], v[174:177], v[198:201], v[48:51]
	v_mfma_f32_16x16x32_bf16 v[44:47], v[182:185], v[198:201], v[44:47]
	v_mfma_f32_16x16x32_bf16 v[32:35], v[174:177], v[218:221], v[32:35]
	v_mfma_f32_16x16x32_bf16 v[28:31], v[182:185], v[218:221], v[28:31]
	v_mfma_f32_16x16x32_bf16 v[16:19], v[174:177], v[226:229], v[16:19]
	v_mfma_f32_16x16x32_bf16 v[12:15], v[182:185], v[226:229], v[12:15]
	s_setprio 0
	s_barrier
; #define PG8_STAGE(bufoff, gbase, voff) do { _Pragma("unroll") for (int _i = 0; _i < 2; ++_i) \
;         __builtin_amdgcn_global_load_lds((const unsigned*)((const char*)(gbase) + (voff)[_i]), (LAS unsigned*)(lds + (bufoff) + ldsw + _i * 8192), 16, 0, 0); } while (0)
; #define PG8_LDA(dst, b, h) do { _Pragma("unroll") for (int m = 0; m < 4; ++m) _Pragma("unroll") for (int k = 0; k < 2; ++k) dst[m][k] = *(const LAS bf16x8*)(lds + PG8_SA(b, h) + aoff + m * 2048 + k * 1024); } while (0)
; #define PG8_LDB(dst, b, h) do { _Pragma("unroll") for (int n = 0; n < 2; ++n) _Pragma("unroll") for (int k = 0; k < 2; ++k) dst[n][k] = *(const LAS bf16x8*)(lds + PG8_SB(b, h) + boff + n * 2048 + k * 1024); } while (0)
; #define PG8_MMA(ai, bj, At, Bt) do { __builtin_amdgcn_s_setprio(1); _Pragma("unroll") for (int m = 0; m < 4; ++m) _Pragma("unroll") for (int n = 0; n < 2; ++n) _Pragma("unroll") for (int k = 0; k < 2; ++k) \
;         acc[ai][bj][m][n] = __builtin_amdgcn_mfma_f32_16x16x32_bf16(Bt[n][k], At[m][k], acc[ai][bj][m][n], 0, 0, 0); __builtin_amdgcn_s_setprio(0); } while (0)
; #define PG8_WAIT_V(n) asm volatile("s_waitcnt vmcnt(" #n ")" ::: "memory")
; #define PG8_WAIT_L(n) asm volatile("s_waitcnt lgkmcnt(" #n ")" ::: "memory")
; #define PG8_BAR __builtin_amdgcn_s_barrier()
; #define PG8_SCHED __builtin_amdgcn_sched_barrier(0)
; template <class Epi>
; __device__ __forceinline__ void gemm_phase(LAS unsigned char* lds, const Gemm g, const StaticOrder& S, const Epi& E) {
;     ...
;             PG8_BAR; PG8_WAIT_L(0); PG8_MMA(1, 0, At, B0); PG8_BAR; PG8_SCHED;
;             PG8_STAGE(PG8_SB(0, 1), b2 + hstep, voffB);
;             PG8_WAIT_V(6); PG8_BAR; PG8_MMA(1, 1, At, B1); PG8_BAR;
;             PG8_LDB(B0, 1, 0); PG8_SCHED; PG8_LDA(At, 1, 0); PG8_STAGE(PG8_SA(0, 1), a2 + hstep, voffA);
;             PG8_WAIT_L(8); PG8_BAR; PG8_WAIT_L(0); PG8_MMA(0, 0, At, B0); PG8_BAR; PG8_SCHED;
;             PG8_LDB(B1, 1, 1); PG8_STAGE(PG8_SB(1, 0), b3, voffB);
;             PG8_BAR; PG8_WAIT_L(0); PG8_MMA(0, 1, At, B1); PG8_BAR;
;             PG8_LDA(At, 1, 1); PG8_STAGE(PG8_SA(1, 0), a3, voffA);
;             PG8_BAR; PG8_WAIT_L(0); PG8_MMA(1, 0, At, B0); PG8_BAR; PG8_SCHED;
	s_add_u32 s72, s22, 0x80000
	s_addc_u32 s73, s23, 0
	s_add_i32 s48, s52, s31
	v_lshl_add_u64 v[142:143], s[72:73], 0, v[148:149]
	s_mov_b32 m0, s48
	s_nop 0
	global_load_lds_dwordx4 v[142:143], off
	v_lshl_add_u64 v[142:143], s[72:73], 0, v[136:137]
	s_add_i32 m0, s48, 0x2000
	s_nop 0
	global_load_lds_dwordx4 v[142:143], off
	s_waitcnt vmcnt(6)
	s_barrier
	s_setprio 1
	v_mfma_f32_16x16x32_bf16 v[56:59], v[230:233], v[186:189], v[56:59]
	v_mfma_f32_16x16x32_bf16 v[52:55], v[238:241], v[186:189], v[52:55]
	v_mfma_f32_16x16x32_bf16 v[40:43], v[230:233], v[194:197], v[40:43]
	v_mfma_f32_16x16x32_bf16 v[36:39], v[238:241], v[194:197], v[36:39]
	v_mfma_f32_16x16x32_bf16 v[24:27], v[230:233], v[214:217], v[24:27]
	v_mfma_f32_16x16x32_bf16 v[20:23], v[238:241], v[214:217], v[20:23]
	v_mfma_f32_16x16x32_bf16 v[8:11], v[230:233], v[222:225], v[8:11]
	v_mfma_f32_16x16x32_bf16 v[4:7], v[238:241], v[222:225], v[4:7]
	v_mfma_f32_16x16x32_bf16 v[56:59], v[234:237], v[190:193], v[56:59]
	v_mfma_f32_16x16x32_bf16 v[52:55], v[242:245], v[190:193], v[52:55]
	v_mfma_f32_16x16x32_bf16 v[40:43], v[234:237], v[198:201], v[40:43]
	v_mfma_f32_16x16x32_bf16 v[36:39], v[242:245], v[198:201], v[36:39]
	v_mfma_f32_16x16x32_bf16 v[24:27], v[234:237], v[218:221], v[24:27]
	v_mfma_f32_16x16x32_bf16 v[20:23], v[242:245], v[218:221], v[20:23]
	v_mfma_f32_16x16x32_bf16 v[8:11], v[234:237], v[226:229], v[8:11]
	v_mfma_f32_16x16x32_bf16 v[4:7], v[242:245], v[226:229], v[4:7]
	s_setprio 0
	s_add_i32 s48, 0, 0x18000
	v_add_u32_e32 v182, s48, v163
	s_barrier
	ds_read_b128 v[142:145], v182
	ds_read_b128 v[174:177], v182 offset:1024
	ds_read_b128 v[178:181], v182 offset:2048
	ds_read_b128 v[182:185], v182 offset:3072
	s_add_u32 s24, s24, 0x80000
	s_addc_u32 s25, s25, 0
	s_mov_b32 m0, s36
	v_lshl_add_u64 v[230:231], s[24:25], 0, v[132:133]
	ds_read_b128 v[186:189], v173 offset:32768
	ds_read_b128 v[190:193], v173 offset:33792
	ds_read_b128 v[194:197], v173 offset:34816
	ds_read_b128 v[198:201], v173 offset:35840
	ds_read_b128 v[214:217], v173 offset:36864
	ds_read_b128 v[218:221], v173 offset:37888
	ds_read_b128 v[222:225], v173 offset:38912
	ds_read_b128 v[226:229], v173 offset:39936
	global_load_lds_dwordx4 v[230:231], off
	v_lshl_add_u64 v[230:231], s[24:25], 0, v[134:135]
	s_mov_b32 m0, s37
	s_nop 0
	global_load_lds_dwordx4 v[230:231], off
	s_waitcnt lgkmcnt(8)
	s_barrier
	s_waitcnt lgkmcnt(0)
	s_setprio 1
	s_waitcnt lgkmcnt(0)
	v_mfma_f32_16x16x32_bf16 v[128:131], v[142:145], v[186:189], v[128:131]
	v_mfma_f32_16x16x32_bf16 v[124:127], v[178:181], v[186:189], v[124:127]
	v_mfma_f32_16x16x32_bf16 v[112:115], v[142:145], v[194:197], v[112:115]
	v_mfma_f32_16x16x32_bf16 v[108:111], v[178:181], v[194:197], v[108:111]
	v_mfma_f32_16x16x32_bf16 v[96:99], v[142:145], v[214:217], v[96:99]
	v_mfma_f32_16x16x32_bf16 v[92:95], v[178:181], v[214:217], v[92:95]
	v_mfma_f32_16x16x32_bf16 v[80:83], v[142:145], v[222:225], v[80:83]
	v_mfma_f32_16x16x32_bf16 v[76:79], v[178:181], v[222:225], v[76:79]
	v_mfma_f32_16x16x32_bf16 v[128:131], v[174:177], v[190:193], v[128:131]
	v_mfma_f32_16x16x32_bf16 v[124:127], v[182:185], v[190:193], v[124:127]
	v_mfma_f32_16x16x32_bf16 v[112:115], v[174:177], v[198:201], v[112:115]
	v_mfma_f32_16x16x32_bf16 v[108:111], v[182:185], v[198:201], v[108:111]
	v_mfma_f32_16x16x32_bf16 v[96:99], v[174:177], v[218:221], v[96:99]
	v_mfma_f32_16x16x32_bf16 v[92:95], v[182:185], v[218:221], v[92:95]
	v_mfma_f32_16x16x32_bf16 v[80:83], v[174:177], v[226:229], v[80:83]
	v_mfma_f32_16x16x32_bf16 v[76:79], v[182:185], v[226:229], v[76:79]
	s_setprio 0
	s_barrier
	s_add_i32 s24, 0, 0x1c000
	s_add_i32 s25, s48, s31
	v_add_u32_e32 v242, s24, v163
	v_lshl_add_u64 v[146:147], v[146:147], 0, s[34:35]
	s_mov_b32 m0, s25
	ds_read_b128 v[230:233], v242
	ds_read_b128 v[234:237], v242 offset:1024
	ds_read_b128 v[238:241], v242 offset:2048
	ds_read_b128 v[242:245], v242 offset:3072
	global_load_lds_dwordx4 v[146:147], off
	v_lshl_add_u64 v[146:147], v[170:171], 0, s[34:35]
	s_add_i32 m0, s25, 0x2000
	s_nop 0
	global_load_lds_dwordx4 v[146:147], off
	s_barrier
	s_waitcnt lgkmcnt(0)
	s_setprio 1
	s_waitcnt lgkmcnt(0)
	v_mfma_f32_16x16x32_bf16 v[120:123], v[230:233], v[186:189], v[120:123]
	v_mfma_f32_16x16x32_bf16 v[116:119], v[238:241], v[186:189], v[116:119]
	v_mfma_f32_16x16x32_bf16 v[104:107], v[230:233], v[194:197], v[104:107]
	v_mfma_f32_16x16x32_bf16 v[100:103], v[238:241], v[194:197], v[100:103]
	v_mfma_f32_16x16x32_bf16 v[88:91], v[230:233], v[214:217], v[88:91]
	v_mfma_f32_16x16x32_bf16 v[84:87], v[238:241], v[214:217], v[84:87]
	v_mfma_f32_16x16x32_bf16 v[72:75], v[230:233], v[222:225], v[72:75]
	v_mfma_f32_16x16x32_bf16 v[68:71], v[238:241], v[222:225], v[68:71]
	v_mfma_f32_16x16x32_bf16 v[120:123], v[234:237], v[190:193], v[120:123]
	v_mfma_f32_16x16x32_bf16 v[116:119], v[242:245], v[190:193], v[116:119]
	v_mfma_f32_16x16x32_bf16 v[104:107], v[234:237], v[198:201], v[104:107]
	v_mfma_f32_16x16x32_bf16 v[100:103], v[242:245], v[198:201], v[100:103]
	v_mfma_f32_16x16x32_bf16 v[88:91], v[234:237], v[218:221], v[88:91]
	v_mfma_f32_16x16x32_bf16 v[84:87], v[242:245], v[218:221], v[84:87]
	v_mfma_f32_16x16x32_bf16 v[72:75], v[234:237], v[226:229], v[72:75]
	v_mfma_f32_16x16x32_bf16 v[68:71], v[242:245], v[226:229], v[68:71]
	s_setprio 0
	s_mov_b32 m0, s38
	v_lshl_add_u64 v[146:147], v[246:247], 0, s[34:35]
	s_barrier
	ds_read_b128 v[186:189], v173 offset:49152
	ds_read_b128 v[190:193], v173 offset:50176
	ds_read_b128 v[194:197], v173 offset:51200
	ds_read_b128 v[198:201], v173 offset:52224
	ds_read_b128 v[214:217], v173 offset:53248
	ds_read_b128 v[218:221], v173 offset:54272
	ds_read_b128 v[222:225], v173 offset:55296
	ds_read_b128 v[226:229], v173 offset:56320
	global_load_lds_dwordx4 v[146:147], off
	v_lshl_add_u64 v[146:147], v[248:249], 0, s[34:35]
	s_mov_b32 m0, s39
	s_nop 0
	global_load_lds_dwordx4 v[146:147], off
	s_barrier
; __device__ __forceinline__ unsigned pack2(float lo, float hi) { unsigned r; asm("v_cvt_pk_bf16_f32 %0, %1, %2" : "=v"(r) : "v"(lo), "v"(hi)); return r; }
; #define PG8_STAGE(bufoff, gbase, voff) do { _Pragma("unroll") for (int _i = 0; _i < 2; ++_i) \
;         __builtin_amdgcn_global_load_lds((const unsigned*)((const char*)(gbase) + (voff)[_i]), (LAS unsigned*)(lds + (bufoff) + ldsw + _i * 8192), 16, 0, 0); } while (0)
; #define PG8_LDA(dst, b, h) do { _Pragma("unroll") for (int m = 0; m < 4; ++m) _Pragma("unroll") for (int k = 0; k < 2; ++k) dst[m][k] = *(const LAS bf16x8*)(lds + PG8_SA(b, h) + aoff + m * 2048 + k * 1024); } while (0)
; #define PG8_WAIT_V(n) asm volatile("s_waitcnt vmcnt(" #n ")" ::: "memory")
; template <class Epi>
; __device__ __forceinline__ void gemm_phase(LAS unsigned char* lds, const Gemm g, const StaticOrder& S, const Epi& E) {
;     ...
;             PG8_WAIT_V(6); PG8_BAR; PG8_MMA(1, 1, At, B1); PG8_BAR;
;             PG8_LDB(B0, 1, 0); PG8_SCHED; PG8_LDA(At, 1, 0); PG8_STAGE(PG8_SA(0, 1), a2 + hstep, voffA);
;             PG8_WAIT_L(8); PG8_BAR; PG8_WAIT_L(0); PG8_MMA(0, 0, At, B0); PG8_BAR; PG8_SCHED;
;             PG8_LDB(B1, 1, 1); PG8_STAGE(PG8_SB(1, 0), b3, voffB);
;             PG8_BAR; PG8_WAIT_L(0); PG8_MMA(0, 1, At, B1); PG8_BAR;
;             PG8_LDA(At, 1, 1); PG8_STAGE(PG8_SA(1, 0), a3, voffA);
;             PG8_BAR; PG8_WAIT_L(0); PG8_MMA(1, 0, At, B0); PG8_BAR; PG8_SCHED;
;             PG8_STAGE(PG8_SB(1, 1), b3 + hstep, voffB);
;             PG8_WAIT_V(6); PG8_BAR; PG8_MMA(1, 1, At, B1); PG8_BAR;
;     __device__ __forceinline__ void operator()(const AccT& acc, const pg8::Unit& u, int wr, int wc, int fr, int fq) const {
;     ...
;         for (int ai = 0; ai < 2; ++ai)
; #pragma unroll
;             for (int m = 0; m < 4; ++m) {
;                 const int row = row0 + ai * 128 + m * 16;
;                 const float r2 = rsqrtf(SS2[row] * (1.f / 2048.f) + EPS);
;                 bf16_t* rowp = UP + (size_t)row * N3 + col0;
; #pragma unroll
;                 for (int bj = 0; bj < 2; ++bj) {
;                     const f32x4 v0 = acc[ai][bj][m][0] * r2, v1 = acc[ai][bj][m][1] * r2;
;                     u32x4 o; o[0] = pack2(v0[0], v0[1]); o[1] = pack2(v0[2], v0[3]); o[2] = pack2(v1[0], v1[1]); o[3] = pack2(v1[2], v1[3]);
;                     *(u32x4*)(rowp + bj * 128) = o;
;                 }
;             }
	s_waitcnt lgkmcnt(0)
	s_setprio 1
	s_waitcnt lgkmcnt(0)
	v_mfma_f32_16x16x32_bf16 v[64:67], v[142:145], v[186:189], v[64:67]
	v_mfma_f32_16x16x32_bf16 v[60:63], v[178:181], v[186:189], v[60:63]
	v_mfma_f32_16x16x32_bf16 v[48:51], v[142:145], v[194:197], v[48:51]
	v_mfma_f32_16x16x32_bf16 v[44:47], v[178:181], v[194:197], v[44:47]
	v_mfma_f32_16x16x32_bf16 v[32:35], v[142:145], v[214:217], v[32:35]
	v_mfma_f32_16x16x32_bf16 v[28:31], v[178:181], v[214:217], v[28:31]
	v_mfma_f32_16x16x32_bf16 v[16:19], v[142:145], v[222:225], v[16:19]
	v_mfma_f32_16x16x32_bf16 v[12:15], v[178:181], v[222:225], v[12:15]
	v_mfma_f32_16x16x32_bf16 v[64:67], v[174:177], v[190:193], v[64:67]
	v_mfma_f32_16x16x32_bf16 v[60:63], v[182:185], v[190:193], v[60:63]
	v_mfma_f32_16x16x32_bf16 v[48:51], v[174:177], v[198:201], v[48:51]
	v_mfma_f32_16x16x32_bf16 v[44:47], v[182:185], v[198:201], v[44:47]
	v_mfma_f32_16x16x32_bf16 v[32:35], v[174:177], v[218:221], v[32:35]
	v_mfma_f32_16x16x32_bf16 v[28:31], v[182:185], v[218:221], v[28:31]
	v_mfma_f32_16x16x32_bf16 v[16:19], v[174:177], v[226:229], v[16:19]
	v_mfma_f32_16x16x32_bf16 v[12:15], v[182:185], v[226:229], v[12:15]
	s_setprio 0
	s_barrier
	s_add_u32 s22, s22, 0x80080
	s_addc_u32 s23, s23, 0
	s_add_i32 s24, s24, s31
	v_lshl_add_u64 v[142:143], s[22:23], 0, v[148:149]
	s_mov_b32 m0, s24
	s_nop 0
	global_load_lds_dwordx4 v[142:143], off
	v_lshl_add_u64 v[142:143], s[22:23], 0, v[136:137]
	s_add_i32 m0, s24, 0x2000
	s_nop 0
	global_load_lds_dwordx4 v[142:143], off
	s_waitcnt vmcnt(6)
	s_barrier
	s_setprio 1
	v_mfma_f32_16x16x32_bf16 v[56:59], v[230:233], v[186:189], v[56:59]
	v_mfma_f32_16x16x32_bf16 v[52:55], v[238:241], v[186:189], v[52:55]
	v_mfma_f32_16x16x32_bf16 v[40:43], v[230:233], v[194:197], v[40:43]
	v_mfma_f32_16x16x32_bf16 v[36:39], v[238:241], v[194:197], v[36:39]
	v_mfma_f32_16x16x32_bf16 v[24:27], v[230:233], v[214:217], v[24:27]
	v_mfma_f32_16x16x32_bf16 v[20:23], v[238:241], v[214:217], v[20:23]
	v_mfma_f32_16x16x32_bf16 v[8:11], v[230:233], v[222:225], v[8:11]
	v_mfma_f32_16x16x32_bf16 v[4:7], v[238:241], v[222:225], v[4:7]
	v_mfma_f32_16x16x32_bf16 v[56:59], v[234:237], v[190:193], v[56:59]
	v_mfma_f32_16x16x32_bf16 v[52:55], v[242:245], v[190:193], v[52:55]
	v_mfma_f32_16x16x32_bf16 v[40:43], v[234:237], v[198:201], v[40:43]
	v_mfma_f32_16x16x32_bf16 v[36:39], v[242:245], v[198:201], v[36:39]
	v_mfma_f32_16x16x32_bf16 v[24:27], v[234:237], v[218:221], v[24:27]
	v_mfma_f32_16x16x32_bf16 v[20:23], v[242:245], v[218:221], v[20:23]
	v_mfma_f32_16x16x32_bf16 v[8:11], v[234:237], v[226:229], v[8:11]
	v_mfma_f32_16x16x32_bf16 v[4:7], v[242:245], v[226:229], v[4:7]
	s_setprio 0
	s_add_i32 s47, s47, 2
	s_add_u32 s20, s20, 0x100
	s_addc_u32 s21, s21, 0
	s_add_u32 s44, s44, 0x100
	s_addc_u32 s46, s46, 0
	s_cmp_gt_u32 s47, 29
	s_barrier
	s_cbranch_scc0 .LBB0_98
	s_mov_b32 s13, 0x800000
	v_lshl_add_u32 v142, s18, 8, v153
	v_ashrrev_i32_e32 v143, 31, v142
	v_lshl_add_u64 v[144:145], v[142:143], 2, s[6:7]
	global_load_dword v246, v[144:145], off
	global_load_dword v247, v[144:145], off offset:64
	global_load_dword v248, v[144:145], off offset:128
	global_load_dword v249, v[144:145], off offset:192
	global_load_dword v250, v[144:145], off offset:512
	global_load_dword v251, v[144:145], off offset:576
	global_load_dword v252, v[144:145], off offset:640
	global_load_dword v253, v[144:145], off offset:704
	v_lshl_or_b32 v170, s41, 8, v172
	v_ashrrev_i32_e32 v171, 31, v170
	s_movk_i32 s9, 0x5800
	v_lshlrev_b64 v[170:171], 1, v[170:171]
	s_mov_b32 s18, s12
	s_mov_b32 s41, s8
	s_mov_b64 s[22:23], s[16:17]
	s_waitcnt vmcnt(0)
	v_mov_b32_e32 v143, v246
	v_fmamk_f32 v143, v143, 0x3a000000, v202
	v_cmp_gt_f32_e32 vcc, s13, v143
	v_mul_f32_e32 v146, 0x4b800000, v143
	s_nop 0
	v_cndmask_b32_e32 v143, v143, v146, vcc
	v_rsq_f32_e32 v143, v143
	s_nop 0
	v_mul_f32_e32 v146, 0x45800000, v143
	v_cndmask_b32_e32 v174, v143, v146, vcc
	v_mov_b64_e32 v[146:147], s[4:5]
	v_mad_i64_i32 v[176:177], s[20:21], v142, s9, v[146:147]
	v_lshl_add_u64 v[176:177], v[176:177], 0, v[170:171]
	v_pk_mul_f32 v[130:131], v[130:131], v[174:175] op_sel_hi:[1,0]
	v_pk_mul_f32 v[128:129], v[128:129], v[174:175] op_sel_hi:[1,0]
	v_pk_mul_f32 v[178:179], v[126:127], v[174:175] op_sel_hi:[1,0]
	v_pk_mul_f32 v[126:127], v[124:125], v[174:175] op_sel_hi:[1,0]
	v_cvt_pk_bf16_f32 v124, v128, v129
	v_cvt_pk_bf16_f32 v125, v130, v131
	v_pk_mul_f32 v[120:121], v[120:121], v[174:175] op_sel_hi:[1,0]
	v_cvt_pk_bf16_f32 v126, v126, v127
	v_cvt_pk_bf16_f32 v127, v178, v179
	global_store_dwordx4 v[176:177], v[124:127], off
	v_pk_mul_f32 v[122:123], v[122:123], v[174:175] op_sel_hi:[1,0]
	s_nop 0
	v_pk_mul_f32 v[124:125], v[118:119], v[174:175] op_sel_hi:[1,0]
	v_pk_mul_f32 v[118:119], v[116:117], v[174:175] op_sel_hi:[1,0]
	v_cvt_pk_bf16_f32 v116, v120, v121
	v_cvt_pk_bf16_f32 v117, v122, v123
	s_nop 0
	v_cvt_pk_bf16_f32 v118, v118, v119
	v_cvt_pk_bf16_f32 v119, v124, v125
	global_store_dwordx4 v[176:177], v[116:119], off offset:256
	s_nop 1
	v_or_b32_e32 v116, 16, v142
	v_ashrrev_i32_e32 v117, 31, v116
	v_lshl_add_u64 v[118:119], v[116:117], 2, s[6:7]
	s_nop 1
	v_mov_b32_e32 v117, v247
	v_fmamk_f32 v117, v117, 0x3a000000, v202
	v_cmp_gt_f32_e32 vcc, s13, v117
	v_mul_f32_e32 v118, 0x4b800000, v117
	s_nop 0
	v_cndmask_b32_e32 v117, v117, v118, vcc
	v_rsq_f32_e32 v117, v117
	s_nop 0
	v_mul_f32_e32 v118, 0x45800000, v117
	v_cndmask_b32_e32 v118, v117, v118, vcc
	v_mad_i64_i32 v[116:117], s[20:21], v116, s9, v[146:147]
	v_lshl_add_u64 v[116:117], v[116:117], 0, v[170:171]
	v_pk_mul_f32 v[114:115], v[114:115], v[118:119] op_sel_hi:[1,0]
; __device__ __forceinline__ unsigned pack2(float lo, float hi) { unsigned r; asm("v_cvt_pk_bf16_f32 %0, %1, %2" : "=v"(r) : "v"(lo), "v"(hi)); return r; }
;     __device__ __forceinline__ void operator()(const AccT& acc, const pg8::Unit& u, int wr, int wc, int fr, int fq) const {
;     ...
;             for (int m = 0; m < 4; ++m) {
;                 const int row = row0 + ai * 128 + m * 16;
;                 const float r2 = rsqrtf(SS2[row] * (1.f / 2048.f) + EPS);
;                 bf16_t* rowp = UP + (size_t)row * N3 + col0;
; #pragma unroll
;                 for (int bj = 0; bj < 2; ++bj) {
;                     const f32x4 v0 = acc[ai][bj][m][0] * r2, v1 = acc[ai][bj][m][1] * r2;
;                     u32x4 o; o[0] = pack2(v0[0], v0[1]); o[1] = pack2(v0[2], v0[3]); o[2] = pack2(v1[0], v1[1]); o[3] = pack2(v1[2], v1[3]);
;                     *(u32x4*)(rowp + bj * 128) = o;
;                 }
;             }
	v_pk_mul_f32 v[112:113], v[112:113], v[118:119] op_sel_hi:[1,0]
	v_pk_mul_f32 v[120:121], v[110:111], v[118:119] op_sel_hi:[1,0]
	v_pk_mul_f32 v[110:111], v[108:109], v[118:119] op_sel_hi:[1,0]
	v_cvt_pk_bf16_f32 v108, v112, v113
	v_cvt_pk_bf16_f32 v109, v114, v115
	v_pk_mul_f32 v[104:105], v[104:105], v[118:119] op_sel_hi:[1,0]
	v_cvt_pk_bf16_f32 v110, v110, v111
	v_cvt_pk_bf16_f32 v111, v120, v121
	global_store_dwordx4 v[116:117], v[108:111], off
	v_pk_mul_f32 v[106:107], v[106:107], v[118:119] op_sel_hi:[1,0]
	s_nop 0
	v_pk_mul_f32 v[108:109], v[102:103], v[118:119] op_sel_hi:[1,0]
	v_pk_mul_f32 v[102:103], v[100:101], v[118:119] op_sel_hi:[1,0]
	v_cvt_pk_bf16_f32 v100, v104, v105
	v_cvt_pk_bf16_f32 v101, v106, v107
	s_nop 0
	v_cvt_pk_bf16_f32 v102, v102, v103
	v_cvt_pk_bf16_f32 v103, v108, v109
	global_store_dwordx4 v[116:117], v[100:103], off offset:256
	s_nop 1
	v_or_b32_e32 v100, 32, v142
	v_ashrrev_i32_e32 v101, 31, v100
	v_lshl_add_u64 v[102:103], v[100:101], 2, s[6:7]
	s_nop 1
	v_mov_b32_e32 v101, v248
	v_fmamk_f32 v101, v101, 0x3a000000, v202
	v_cmp_gt_f32_e32 vcc, s13, v101
	v_mul_f32_e32 v102, 0x4b800000, v101
	s_nop 0
	v_cndmask_b32_e32 v101, v101, v102, vcc
	v_rsq_f32_e32 v101, v101
	s_nop 0
	v_mul_f32_e32 v102, 0x45800000, v101
	v_cndmask_b32_e32 v102, v101, v102, vcc
	v_mad_i64_i32 v[100:101], s[20:21], v100, s9, v[146:147]
	v_lshl_add_u64 v[100:101], v[100:101], 0, v[170:171]
	v_pk_mul_f32 v[98:99], v[98:99], v[102:103] op_sel_hi:[1,0]
	v_pk_mul_f32 v[96:97], v[96:97], v[102:103] op_sel_hi:[1,0]
	v_pk_mul_f32 v[104:105], v[94:95], v[102:103] op_sel_hi:[1,0]
	v_pk_mul_f32 v[94:95], v[92:93], v[102:103] op_sel_hi:[1,0]
	v_cvt_pk_bf16_f32 v92, v96, v97
	v_cvt_pk_bf16_f32 v93, v98, v99
	v_pk_mul_f32 v[88:89], v[88:89], v[102:103] op_sel_hi:[1,0]
	v_cvt_pk_bf16_f32 v94, v94, v95
	v_cvt_pk_bf16_f32 v95, v104, v105
	global_store_dwordx4 v[100:101], v[92:95], off
	v_pk_mul_f32 v[90:91], v[90:91], v[102:103] op_sel_hi:[1,0]
	s_nop 0
	v_pk_mul_f32 v[92:93], v[86:87], v[102:103] op_sel_hi:[1,0]
	v_pk_mul_f32 v[86:87], v[84:85], v[102:103] op_sel_hi:[1,0]
	v_cvt_pk_bf16_f32 v84, v88, v89
	v_cvt_pk_bf16_f32 v85, v90, v91
	s_nop 0
	v_cvt_pk_bf16_f32 v86, v86, v87
	v_cvt_pk_bf16_f32 v87, v92, v93
	global_store_dwordx4 v[100:101], v[84:87], off offset:256
	s_nop 1
	v_or_b32_e32 v84, 48, v142
	v_ashrrev_i32_e32 v85, 31, v84
	v_lshl_add_u64 v[86:87], v[84:85], 2, s[6:7]
	s_nop 1
	v_mov_b32_e32 v85, v249
	v_fmamk_f32 v85, v85, 0x3a000000, v202
	v_cmp_gt_f32_e32 vcc, s13, v85
	v_mul_f32_e32 v86, 0x4b800000, v85
	s_nop 0
	v_cndmask_b32_e32 v85, v85, v86, vcc
	v_rsq_f32_e32 v85, v85
	s_nop 0
	v_mul_f32_e32 v86, 0x45800000, v85
	v_cndmask_b32_e32 v86, v85, v86, vcc
	v_mad_i64_i32 v[84:85], s[20:21], v84, s9, v[146:147]
	v_lshl_add_u64 v[84:85], v[84:85], 0, v[170:171]
	v_pk_mul_f32 v[82:83], v[82:83], v[86:87] op_sel_hi:[1,0]
	v_pk_mul_f32 v[80:81], v[80:81], v[86:87] op_sel_hi:[1,0]
	v_pk_mul_f32 v[88:89], v[78:79], v[86:87] op_sel_hi:[1,0]
	v_pk_mul_f32 v[78:79], v[76:77], v[86:87] op_sel_hi:[1,0]
	v_cvt_pk_bf16_f32 v76, v80, v81
	v_cvt_pk_bf16_f32 v77, v82, v83
	v_pk_mul_f32 v[74:75], v[74:75], v[86:87] op_sel_hi:[1,0]
	v_cvt_pk_bf16_f32 v78, v78, v79
	v_cvt_pk_bf16_f32 v79, v88, v89
	global_store_dwordx4 v[84:85], v[76:79], off
	v_pk_mul_f32 v[72:73], v[72:73], v[86:87] op_sel_hi:[1,0]
	s_nop 0
	v_pk_mul_f32 v[76:77], v[70:71], v[86:87] op_sel_hi:[1,0]
	v_pk_mul_f32 v[70:71], v[68:69], v[86:87] op_sel_hi:[1,0]
	v_cvt_pk_bf16_f32 v68, v72, v73
	v_cvt_pk_bf16_f32 v69, v74, v75
	s_nop 0
	v_cvt_pk_bf16_f32 v70, v70, v71
	v_cvt_pk_bf16_f32 v71, v76, v77
	global_store_dwordx4 v[84:85], v[68:71], off offset:256
	s_nop 1
	v_mov_b32_e32 v68, v250
	s_nop 0
	v_add_u32_e32 v69, 0x80, v142
	v_fmamk_f32 v68, v68, 0x3a000000, v202
	v_cmp_gt_f32_e32 vcc, s13, v68
	v_mul_f32_e32 v70, 0x4b800000, v68
	s_nop 0
	v_cndmask_b32_e32 v68, v68, v70, vcc
	v_rsq_f32_e32 v68, v68
	s_nop 0
	v_mul_f32_e32 v70, 0x45800000, v68
	v_cndmask_b32_e32 v68, v68, v70, vcc
	v_mad_i64_i32 v[70:71], s[20:21], v69, s9, v[146:147]
	v_lshl_add_u64 v[70:71], v[70:71], 0, v[170:171]
	v_pk_mul_f32 v[66:67], v[66:67], v[68:69] op_sel_hi:[1,0]
	v_pk_mul_f32 v[64:65], v[64:65], v[68:69] op_sel_hi:[1,0]
	v_pk_mul_f32 v[72:73], v[62:63], v[68:69] op_sel_hi:[1,0]
	v_pk_mul_f32 v[62:63], v[60:61], v[68:69] op_sel_hi:[1,0]
	v_cvt_pk_bf16_f32 v60, v64, v65
	v_cvt_pk_bf16_f32 v61, v66, v67
	v_pk_mul_f32 v[58:59], v[58:59], v[68:69] op_sel_hi:[1,0]
	v_cvt_pk_bf16_f32 v62, v62, v63
; __device__ __forceinline__ unsigned pack2(float lo, float hi) { unsigned r; asm("v_cvt_pk_bf16_f32 %0, %1, %2" : "=v"(r) : "v"(lo), "v"(hi)); return r; }
;     __device__ __forceinline__ void operator()(const AccT& acc, const pg8::Unit& u, int wr, int wc, int fr, int fq) const {
;     ...
;             for (int m = 0; m < 4; ++m) {
;                 const int row = row0 + ai * 128 + m * 16;
;                 const float r2 = rsqrtf(SS2[row] * (1.f / 2048.f) + EPS);
;                 bf16_t* rowp = UP + (size_t)row * N3 + col0;
; #pragma unroll
;                 for (int bj = 0; bj < 2; ++bj) {
;                     const f32x4 v0 = acc[ai][bj][m][0] * r2, v1 = acc[ai][bj][m][1] * r2;
;                     u32x4 o; o[0] = pack2(v0[0], v0[1]); o[1] = pack2(v0[2], v0[3]); o[2] = pack2(v1[0], v1[1]); o[3] = pack2(v1[2], v1[3]);
;                     *(u32x4*)(rowp + bj * 128) = o;
;                 }
;             }
	v_cvt_pk_bf16_f32 v63, v72, v73
	global_store_dwordx4 v[70:71], v[60:63], off
	v_pk_mul_f32 v[56:57], v[56:57], v[68:69] op_sel_hi:[1,0]
	s_nop 0
	v_pk_mul_f32 v[60:61], v[54:55], v[68:69] op_sel_hi:[1,0]
	v_pk_mul_f32 v[54:55], v[52:53], v[68:69] op_sel_hi:[1,0]
	v_cvt_pk_bf16_f32 v52, v56, v57
	v_cvt_pk_bf16_f32 v53, v58, v59
	s_nop 0
	v_cvt_pk_bf16_f32 v54, v54, v55
	v_cvt_pk_bf16_f32 v55, v60, v61
	global_store_dwordx4 v[70:71], v[52:55], off offset:256
	s_nop 1
	v_mov_b32_e32 v52, v251
	s_nop 0
	v_add_u32_e32 v53, 0x90, v142
	v_fmamk_f32 v52, v52, 0x3a000000, v202
	v_cmp_gt_f32_e32 vcc, s13, v52
	v_mul_f32_e32 v54, 0x4b800000, v52
	s_nop 0
	v_cndmask_b32_e32 v52, v52, v54, vcc
	v_rsq_f32_e32 v52, v52
	s_nop 0
	v_mul_f32_e32 v54, 0x45800000, v52
	v_cndmask_b32_e32 v52, v52, v54, vcc
	v_mad_i64_i32 v[54:55], s[20:21], v53, s9, v[146:147]
	v_lshl_add_u64 v[54:55], v[54:55], 0, v[170:171]
	v_pk_mul_f32 v[50:51], v[50:51], v[52:53] op_sel_hi:[1,0]
	v_pk_mul_f32 v[48:49], v[48:49], v[52:53] op_sel_hi:[1,0]
	v_pk_mul_f32 v[56:57], v[46:47], v[52:53] op_sel_hi:[1,0]
	v_pk_mul_f32 v[46:47], v[44:45], v[52:53] op_sel_hi:[1,0]
	v_cvt_pk_bf16_f32 v44, v48, v49
	v_cvt_pk_bf16_f32 v45, v50, v51
	v_pk_mul_f32 v[42:43], v[42:43], v[52:53] op_sel_hi:[1,0]
	v_cvt_pk_bf16_f32 v46, v46, v47
	v_cvt_pk_bf16_f32 v47, v56, v57
	global_store_dwordx4 v[54:55], v[44:47], off
	v_pk_mul_f32 v[40:41], v[40:41], v[52:53] op_sel_hi:[1,0]
	s_nop 0
	v_pk_mul_f32 v[44:45], v[38:39], v[52:53] op_sel_hi:[1,0]
	v_pk_mul_f32 v[38:39], v[36:37], v[52:53] op_sel_hi:[1,0]
	v_cvt_pk_bf16_f32 v36, v40, v41
	v_cvt_pk_bf16_f32 v37, v42, v43
	s_nop 0
	v_cvt_pk_bf16_f32 v38, v38, v39
	v_cvt_pk_bf16_f32 v39, v44, v45
	global_store_dwordx4 v[54:55], v[36:39], off offset:256
	s_nop 1
	v_mov_b32_e32 v36, v252
	s_nop 0
	v_add_u32_e32 v37, 0xa0, v142
	v_fmamk_f32 v36, v36, 0x3a000000, v202
	v_cmp_gt_f32_e32 vcc, s13, v36
	v_mul_f32_e32 v38, 0x4b800000, v36
	s_nop 0
	v_cndmask_b32_e32 v36, v36, v38, vcc
	v_rsq_f32_e32 v36, v36
	s_nop 0
	v_mul_f32_e32 v38, 0x45800000, v36
	v_cndmask_b32_e32 v36, v36, v38, vcc
	v_mad_i64_i32 v[38:39], s[20:21], v37, s9, v[146:147]
	v_lshl_add_u64 v[38:39], v[38:39], 0, v[170:171]
	v_pk_mul_f32 v[34:35], v[34:35], v[36:37] op_sel_hi:[1,0]
	v_pk_mul_f32 v[32:33], v[32:33], v[36:37] op_sel_hi:[1,0]
	v_pk_mul_f32 v[40:41], v[30:31], v[36:37] op_sel_hi:[1,0]
	v_pk_mul_f32 v[30:31], v[28:29], v[36:37] op_sel_hi:[1,0]
	v_cvt_pk_bf16_f32 v28, v32, v33
	v_cvt_pk_bf16_f32 v29, v34, v35
	v_pk_mul_f32 v[26:27], v[26:27], v[36:37] op_sel_hi:[1,0]
	v_cvt_pk_bf16_f32 v30, v30, v31
	v_cvt_pk_bf16_f32 v31, v40, v41
	global_store_dwordx4 v[38:39], v[28:31], off
	v_pk_mul_f32 v[24:25], v[24:25], v[36:37] op_sel_hi:[1,0]
	s_nop 0
	v_pk_mul_f32 v[28:29], v[22:23], v[36:37] op_sel_hi:[1,0]
	v_pk_mul_f32 v[22:23], v[20:21], v[36:37] op_sel_hi:[1,0]
	v_cvt_pk_bf16_f32 v20, v24, v25
	v_cvt_pk_bf16_f32 v21, v26, v27
	s_nop 0
	v_cvt_pk_bf16_f32 v22, v22, v23
	v_cvt_pk_bf16_f32 v23, v28, v29
	global_store_dwordx4 v[38:39], v[20:23], off offset:256
	s_nop 1
	v_mov_b32_e32 v20, v253
	s_nop 0
	v_add_u32_e32 v21, 0xb0, v142
	v_fmamk_f32 v20, v20, 0x3a000000, v202
	v_cmp_gt_f32_e32 vcc, s13, v20
	v_mul_f32_e32 v22, 0x4b800000, v20
	s_nop 0
	v_cndmask_b32_e32 v20, v20, v22, vcc
	v_rsq_f32_e32 v20, v20
	s_nop 0
	v_mul_f32_e32 v22, 0x45800000, v20
	v_cndmask_b32_e32 v20, v20, v22, vcc
	v_mad_i64_i32 v[22:23], s[20:21], v21, s9, v[146:147]
	v_lshl_add_u64 v[22:23], v[22:23], 0, v[170:171]
	v_pk_mul_f32 v[18:19], v[18:19], v[20:21] op_sel_hi:[1,0]
	v_pk_mul_f32 v[16:17], v[16:17], v[20:21] op_sel_hi:[1,0]
	v_pk_mul_f32 v[24:25], v[14:15], v[20:21] op_sel_hi:[1,0]
	v_pk_mul_f32 v[14:15], v[12:13], v[20:21] op_sel_hi:[1,0]
	v_cvt_pk_bf16_f32 v12, v16, v17
	v_cvt_pk_bf16_f32 v13, v18, v19
	s_and_b64 vcc, exec, s[0:1]
	v_cvt_pk_bf16_f32 v14, v14, v15
	v_cvt_pk_bf16_f32 v15, v24, v25
	global_store_dwordx4 v[22:23], v[12:15], off
	s_mov_b64 s[20:21], s[14:15]
	v_pk_mul_f32 v[10:11], v[10:11], v[20:21] op_sel_hi:[1,0]
	v_pk_mul_f32 v[12:13], v[6:7], v[20:21] op_sel_hi:[1,0]
	v_pk_mul_f32 v[6:7], v[4:5], v[20:21] op_sel_hi:[1,0]
	v_pk_mul_f32 v[8:9], v[8:9], v[20:21] op_sel_hi:[1,0]
	v_cvt_pk_bf16_f32 v5, v10, v11
	v_cvt_pk_bf16_f32 v6, v6, v7
	v_cvt_pk_bf16_f32 v7, v12, v13
	s_nop 0
	v_cvt_pk_bf16_f32 v4, v8, v9
	global_store_dwordx4 v[22:23], v[4:7], off offset:256
	s_cbranch_vccz .LBB0_91
	s_waitcnt vmcnt(0)
	s_mov_b32 s47, s50
	s_cmpk_gt_u32 s27, 0xff
	s_cbranch_scc1 .LBB0_102
	s_barrier
